# retention: V-tile DMAs 1-3 issued in the pack window after the last S MFMA instead of between S-phase MFMAs
# baseline (speedup 1.0000x reference)
; #define LAS __attribute__((address_space(3)))
; __device__ __forceinline__ void p2_ret(const Frame& F, ArgsP a, int layer) {
;     ...
;                 { const LAS unsigned char* kb = lds + RT_K0 + bf * 32768 + (32 * wc + kap) * 512;
;     ...
;                   bf16x8 ka[2], kd[2], kc[2];
;                   RT_KRD(ka, 0); RT_KRD(kd, 2); __builtin_amdgcn_sched_barrier(0);
;                   RT_KRD(kc, 4); RT_KMM(ka, 0); if (pre) { RT_DMA_K(kt + 1, bf ^ 1, 0); RT_DMA_V(kt + 1, bf ^ 1, 0); } __builtin_amdgcn_sched_barrier(0);
;                   RT_KRD(ka, 6); RT_KMM(kd, 2); __builtin_amdgcn_sched_barrier(0);
;                   RT_KRD(kd, 8); RT_KMM(kc, 4); if (pre) { RT_DMA_K(kt + 1, bf ^ 1, 1); RT_DMA_V(kt + 1, bf ^ 1, 1); } __builtin_amdgcn_sched_barrier(0);
;                   RT_KRD(kc, 10); RT_KMM(ka, 6); __builtin_amdgcn_sched_barrier(0);
;                   RT_KRD(ka, 12); RT_KMM(kd, 8); if (pre) { RT_DMA_K(kt + 1, bf ^ 1, 2); RT_DMA_V(kt + 1, bf ^ 1, 2); } __builtin_amdgcn_sched_barrier(0);
;                   RT_KRD(kd, 14); RT_KMM(kc, 10); __builtin_amdgcn_sched_barrier(0);
;                   RT_KMM(ka, 12); if (pre) { RT_DMA_K(kt + 1, bf ^ 1, 3); RT_DMA_V(kt + 1, bf ^ 1, 3); } __builtin_amdgcn_sched_barrier(0);
;                   RT_KMM(kd, 14); __builtin_amdgcn_sched_barrier(0);
;     ...
;                 }
;                 { const bool diag = kt >= 2 * qi;
;                   unsigned pk[8];
;                   if (!diag) { const float tf = __builtin_amdgcn_exp2f((float)(128 * (qi - (kt >> 1))) * lg2);
; #pragma unroll
;                       for (int i = 0; i < 8; ++i) pk[i] = cvt_pk_bf16(st[2 * i] * tf, st[2 * i + 1] * tf);
;                   } else { const int lim = wr * 32 + l31 + (2 * qi - kt) * 64 - 32 * wc - 8 * hh;
; #pragma unroll
;                       for (int i = 0; i < 8; ++i) { const int r0 = 2 * i, r1 = 2 * i + 1, o0 = 16 * (r0 >> 3) + (r0 & 7), o1 = 16 * (r1 >> 3) + (r1 & 7);
;                           pk[i] = cvt_pk_bf16((o0 <= lim) ? st[r0] : 0.f, (o1 <= lim) ? st[r1] : 0.f); } }
;                   LAS unsigned char* pw = lds + RT_P + ((wr * 2 + wc) * 2) * 1024 + lane * 16;
;                   *(LAS u32x4*)pw = (u32x4){pk[0], pk[1], pk[2], pk[3]}; *(LAS u32x4*)(pw + 1024) = (u32x4){pk[4], pk[5], pk[6], pk[7]}; }
.LBB0_383:
	v_mov_b32_e32 v0, v207
	s_and_b32 s6, s31, 0x8000
	v_lshlrev_b32_e32 v99, 1, v0
	v_lshrrev_b32_e32 v100, 1, v0
	v_and_b32_e32 v98, 19, v0
	v_and_b32_e32 v99, 8, v99
	v_and_b32_e32 v100, 4, v100
	v_or3_b32 v115, v99, v98, v100
	v_ashrrev_i32_e32 v116, 5, v0
	s_add_i32 s4, s6, 0
	v_or_b32_e32 v98, s80, v115
	v_lshl_add_u32 v227, v98, 9, s4
	v_bitop3_b32 v228, v115, v116, 15 bitop3:0x6c
	v_or_b32_e32 v229, 2, v116
	v_bitop3_b32 v229, v115, v229, 15 bitop3:0x6c
	v_lshl_add_u32 v228, v228, 4, v227
	v_lshl_add_u32 v229, v229, 4, v227
	ds_read_b128 v[98:101], v228
	ds_read_b128 v[190:193], v229
	v_or_b32_e32 v230, 4, v116
	v_bitop3_b32 v230, v115, v230, 15 bitop3:0x6c
	v_or_b32_e32 v231, 6, v116
	v_lshl_add_u32 v230, v230, 4, v227
	v_bitop3_b32 v231, v115, v231, 15 bitop3:0x6c
	v_lshl_add_u32 v231, v231, 4, v227
	ds_read_b128 v[194:197], v230
	ds_read_b128 v[198:201], v231
	v_and_b32_e32 v117, 31, v0
	v_or_b32_e32 v250, 8, v116
	s_xor_b32 s4, s6, 0x8000
	v_bitop3_b32 v250, v115, v250, 15 bitop3:0x6c
	v_or_b32_e32 v251, 10, v116
	s_add_i32 s5, s22, s4
	v_lshl_add_u32 v250, v250, 4, v227
	v_bitop3_b32 v251, v115, v251, 15 bitop3:0x6c
	v_lshl_add_u32 v251, v251, 4, v227
	ds_read_b128 v[202:205], v250
	ds_read_b128 v[212:215], v251
	s_add_i32 s7, s25, s30
	s_add_i32 m0, s33, s4
	s_add_i32 s12, s7, 0x80
	s_mov_b32 s46, s42
	s_mov_b32 s47, s43
	buffer_load_dwordx4 v225, s[44:47], s12 offen lds
	s_waitcnt lgkmcnt(5)
	v_mfma_f32_32x32x16_bf16 v[98:113], v[98:101], v[118:121], 0
	s_waitcnt lgkmcnt(4)
	v_mfma_f32_32x32x16_bf16 v[98:113], v[190:193], v[122:125], v[98:113]
	v_or_b32_e32 v252, 12, v116
	v_or_b32_e32 v253, 14, v116
	v_bitop3_b32 v252, v115, v252, 15 bitop3:0x6c
	v_bitop3_b32 v253, v115, v253, 15 bitop3:0x6c
	v_lshl_add_u32 v252, v252, 4, v227
	v_lshl_add_u32 v253, v253, 4, v227
	ds_read_b128 v[190:193], v252
	ds_read_b128 v[216:219], v253
	s_waitcnt lgkmcnt(5)
	v_mfma_f32_32x32x16_bf16 v[98:113], v[194:197], v[126:129], v[98:113]
	s_add_i32 s4, s4, 0
	s_waitcnt lgkmcnt(4)
	v_mfma_f32_32x32x16_bf16 v[98:113], v[198:201], v[130:133], v[98:113]
	s_add_i32 s12, s27, 0xfffe0000
	s_add_i32 s4, s4, 0x10000
	ds_read_b128 v[194:197], v228 offset:256
	ds_read_b128 v[198:201], v229 offset:256
	s_waitcnt lgkmcnt(5)
	v_mfma_f32_32x32x16_bf16 v[98:113], v[202:205], v[134:137], v[98:113]
	s_waitcnt lgkmcnt(4)
	v_mfma_f32_32x32x16_bf16 v[98:113], v[212:215], v[138:141], v[98:113]
	ds_read_b128 v[202:205], v230 offset:256
	ds_read_b128 v[212:215], v231 offset:256
	s_waitcnt lgkmcnt(5)
	v_mfma_f32_32x32x16_bf16 v[98:113], v[190:193], v[142:145], v[98:113]
	s_add_i32 s12, s27, 0xffff0000
	s_waitcnt lgkmcnt(4)
	v_mfma_f32_32x32x16_bf16 v[98:113], v[216:219], v[146:149], v[98:113]
	ds_read_b128 v[190:193], v250 offset:256
	ds_read_b128 v[216:219], v251 offset:256
	s_waitcnt lgkmcnt(5)
	v_mfma_f32_32x32x16_bf16 v[98:113], v[194:197], v[150:153], v[98:113]
	s_waitcnt lgkmcnt(4)
	v_mfma_f32_32x32x16_bf16 v[98:113], v[198:201], v[154:157], v[98:113]
	s_waitcnt lgkmcnt(3)
	v_mfma_f32_32x32x16_bf16 v[98:113], v[202:205], v[158:161], v[98:113]
	ds_read_b128 v[194:197], v252 offset:256
	ds_read_b128 v[198:201], v253 offset:256
	s_waitcnt lgkmcnt(4)
	v_mfma_f32_32x32x16_bf16 v[98:113], v[212:215], v[162:165], v[98:113]
	s_waitcnt lgkmcnt(3)
	v_mfma_f32_32x32x16_bf16 v[98:113], v[190:193], v[166:169], v[98:113]
	s_waitcnt lgkmcnt(2)
	v_mfma_f32_32x32x16_bf16 v[98:113], v[216:219], v[170:173], v[98:113]
	s_waitcnt lgkmcnt(1)
	v_mfma_f32_32x32x16_bf16 v[98:113], v[194:197], v[174:177], v[98:113]
	s_waitcnt lgkmcnt(0)
	v_mfma_f32_32x32x16_bf16 v[98:113], v[198:201], v[178:181], v[98:113]
	s_add_i32 m0, s4, s24
	s_add_i32 s12, s7, 0x100080
	buffer_load_dwordx4 v225, s[44:47], s12 offen lds
	s_add_i32 m0, s4, s26
	s_add_i32 s12, s7, 0x200080
	buffer_load_dwordx4 v225, s[44:47], s12 offen lds
	s_add_i32 m0, s4, s28
	s_add_i32 s7, s7, 0x300080
	buffer_load_dwordx4 v225, s[44:47], s7 offen lds
	v_lshlrev_b32_e32 v250, 3, v115
	v_and_b32_e32 v250, 0x70, v250
	s_add_i32 s13, s64, s6
	v_lshl_add_u32 v251, v115, 7, s13
	v_lshlrev_b32_e32 v252, 4, v116
	s_lshl_b32 s14, s80, 1
	v_xad_u32 v246, v250, v252, v251
	v_add_u32_e32 v253, 32, v252
	v_xad_u32 v247, v250, v253, v251
	v_xor_b32_e32 v246, s14, v246
	v_xor_b32_e32 v247, s14, v247
	v_xor_b32_e32 v248, 64, v246
	v_xor_b32_e32 v249, 64, v247
	ds_read_b128 v[234:237], v246
	ds_read_b128 v[238:241], v247
	s_cmp_ge_u32 s91, s29
	s_mov_b64 s[4:5], -1
	s_cbranch_scc0 .LBB0_385
	v_lshlrev_b32_e32 v190, 3, v116
	v_sub_u32_e32 v117, v117, v190
	v_add_u32_e32 v117, s97, v117
	v_cmp_lt_i32_e32 vcc, -1, v117
	s_mov_b64 s[4:5], 0
	s_nop 3
	v_cndmask_b32_e32 v190, 0, v98, vcc
	v_cmp_lt_i32_e32 vcc, 0, v117
	s_nop 1
	v_cndmask_b32_e32 v191, 0, v99, vcc
	v_cmp_lt_i32_e32 vcc, 1, v117
	v_cvt_pk_bf16_f32 v190, v190, v191
	s_nop 1
	v_cndmask_b32_e32 v191, 0, v100, vcc
	v_cmp_lt_i32_e32 vcc, 2, v117
	s_nop 1
	v_cndmask_b32_e32 v192, 0, v101, vcc
	v_cmp_lt_i32_e32 vcc, 3, v117
	v_cvt_pk_bf16_f32 v191, v191, v192
	s_nop 1
	v_cndmask_b32_e32 v192, 0, v102, vcc
	v_cmp_lt_i32_e32 vcc, 4, v117
	s_nop 1
	v_cndmask_b32_e32 v193, 0, v103, vcc
	v_cmp_lt_i32_e32 vcc, 5, v117
	v_cvt_pk_bf16_f32 v192, v192, v193
	s_nop 1
	v_cndmask_b32_e32 v193, 0, v104, vcc
	v_cmp_lt_i32_e32 vcc, 6, v117
	s_nop 1
	v_cndmask_b32_e32 v194, 0, v105, vcc
	v_cmp_lt_i32_e32 vcc, 15, v117
	v_cvt_pk_bf16_f32 v193, v193, v194
	s_nop 1
	v_cndmask_b32_e32 v194, 0, v106, vcc
	v_cmp_lt_i32_e32 vcc, 16, v117
	s_nop 1
	v_cndmask_b32_e32 v195, 0, v107, vcc
	v_cmp_lt_i32_e32 vcc, 17, v117
	v_cvt_pk_bf16_f32 v194, v194, v195
	s_nop 1
	v_cndmask_b32_e32 v195, 0, v108, vcc
	v_cmp_lt_i32_e32 vcc, 18, v117
	s_nop 1
	v_cndmask_b32_e32 v196, 0, v109, vcc
	v_cmp_lt_i32_e32 vcc, 19, v117
	v_cvt_pk_bf16_f32 v195, v195, v196
	s_nop 1
	v_cndmask_b32_e32 v196, 0, v110, vcc
	v_cmp_lt_i32_e32 vcc, 20, v117
	s_nop 1
	v_cndmask_b32_e32 v197, 0, v111, vcc
	v_cmp_lt_i32_e32 vcc, 21, v117
	v_cvt_pk_bf16_f32 v196, v196, v197
	s_nop 1
	v_cndmask_b32_e32 v197, 0, v112, vcc
	v_cmp_lt_i32_e32 vcc, 22, v117
	s_nop 1
	v_cndmask_b32_e32 v117, 0, v113, vcc
	v_cvt_pk_bf16_f32 v197, v197, v117
